# in-proj K-loop staging DMA in scalar-base form (16 64-bit VALU address adds per iteration removed), on top of dsaddr
# baseline (speedup 1.0000x reference)
; #define PG8_STAGE(bufoff, gbase, voff) do { _Pragma("unroll") for (int _i = 0; _i < 2; ++_i) \
;         __builtin_amdgcn_global_load_lds((const unsigned*)((const char*)(gbase) + (voff)[_i]), (PG8_LAS unsigned*)(lds + (bufoff) + ldsw + _i * 8192), 16, 0, 0); } while (0)
; #define PG8_LDA(dst, b, h) do { _Pragma("unroll") for (int m = 0; m < 4; ++m) _Pragma("unroll") for (int k = 0; k < 2; ++k) dst[m][k] = *(const PG8_LAS bf16x8*)(lds + PG8_SA(b, h) + aoff + m * 2048 + k * 1024); } while (0)
; #define PG8_LDB(dst, b, h) do { _Pragma("unroll") for (int n = 0; n < 2; ++n) _Pragma("unroll") for (int k = 0; k < 2; ++k) dst[n][k] = *(const PG8_LAS bf16x8*)(lds + PG8_SB(b, h) + boff + n * 2048 + k * 1024); } while (0)
; #define PG8_MMA(ai, bj, At, Bt) do { __builtin_amdgcn_s_setprio(1); _Pragma("unroll") for (int m = 0; m < 4; ++m) _Pragma("unroll") for (int n = 0; n < 2; ++n) _Pragma("unroll") for (int k = 0; k < 2; ++k) \
;         acc[ai][bj][m][n] = __builtin_amdgcn_mfma_f32_16x16x32_bf16(Bt[n][k], At[m][k], acc[ai][bj][m][n], 0, 0, 0); __builtin_amdgcn_s_setprio(0); } while (0)
; #define PG8_WAIT_V(n) asm volatile("s_waitcnt vmcnt(" #n ")" ::: "memory")
; #define PG8_WAIT_L(n) asm volatile("s_waitcnt lgkmcnt(" #n ")" ::: "memory")
; #define PG8_BAR __builtin_amdgcn_s_barrier()
; #define PG8_SCHED __builtin_amdgcn_sched_barrier(0)
; template <class Epi, class Sched, bool ALIGN_EPI = false, bool SP2 = false>
; __device__ __forceinline__ void gemm_phase(PG8_LAS unsigned char* lds, const Gemm g, const Sched& S, const Epi& E) {
;     ...
;             PG8_LDB(B0, 0, 0); PG8_LDB(B1, 0, 1); PG8_SCHED; PG8_LDA(At, 0, 0); PG8_STAGE(PG8_SA(1, 1), a1 + hstep, voffA);
;             PG8_WAIT_V(8); PG8_WAIT_L(0); PG8_BAR; PG8_MMA(0, 0, At, B0); PG8_MMA(0, 1, At, B1); PG8_BAR; PG8_SCHED;
;             PG8_LDA(At, 0, 1); PG8_STAGE(PG8_SB(0, 0), b2, voffB); PG8_STAGE(PG8_SB(0, 1), b2 + hstep, voffB); PG8_STAGE(PG8_SA(0, 0), a2, voffA);
;             PG8_WAIT_V(8); PG8_WAIT_L(0); PG8_BAR; PG8_MMA(1, 0, At, B0); PG8_MMA(1, 1, At, B1); PG8_BAR; PG8_SCHED;
.LBB0_214:
	ds_read_b128 v[114:117], v242
	ds_read_b128 v[118:121], v242 offset:1024
	ds_read_b128 v[130:133], v242 offset:2048
	ds_read_b128 v[134:137], v242 offset:3072
	ds_read_b128 v[146:149], v243
	ds_read_b128 v[150:153], v243 offset:1024
	ds_read_b128 v[168:171], v243 offset:2048
	ds_read_b128 v[172:175], v243 offset:3072
	s_add_u32 s40, s34, 0xfff80080
	s_addc_u32 s41, s35, -1
	s_cmp_eq_u32 s46, 28
	s_cselect_b32 s43, s15, s41
	s_cselect_b32 s42, s19, s40
	s_cselect_b32 s41, s17, s45
	s_cselect_b32 s40, s37, s44
	s_add_i32 m0, s8, 0xc000
	ds_read_b128 v[180:183], v178
	ds_read_b128 v[184:187], v178 offset:1024
	ds_read_b128 v[188:191], v178 offset:2048
	ds_read_b128 v[192:195], v178 offset:3072
	ds_read_b128 v[196:199], v178 offset:4096
	ds_read_b128 v[200:203], v178 offset:5120
	ds_read_b128 v[208:211], v178 offset:6144
	ds_read_b128 v[230:233], v178 offset:7168
	global_load_lds_dwordx4 v164, s[34:35]
	s_add_i32 m0, s8, 0xe000
	s_nop 0
	global_load_lds_dwordx4 v166, s[34:35]
	s_waitcnt vmcnt(8)
	s_waitcnt lgkmcnt(0)
	s_barrier
	s_setprio 1
	v_mfma_f32_16x16x32_bf16 v[142:145], v[114:117], v[180:183], v[142:145]
	v_mfma_f32_16x16x32_bf16 v[138:141], v[130:133], v[180:183], v[138:141]
	v_mfma_f32_16x16x32_bf16 v[110:113], v[114:117], v[188:191], v[110:113]
	v_mfma_f32_16x16x32_bf16 v[106:109], v[130:133], v[188:191], v[106:109]
	v_mfma_f32_16x16x32_bf16 v[94:97], v[114:117], v[196:199], v[94:97]
	v_mfma_f32_16x16x32_bf16 v[90:93], v[130:133], v[196:199], v[90:93]
	v_mfma_f32_16x16x32_bf16 v[78:81], v[114:117], v[208:211], v[78:81]
	v_mfma_f32_16x16x32_bf16 v[74:77], v[130:133], v[208:211], v[74:77]
	v_mfma_f32_16x16x32_bf16 v[142:145], v[118:121], v[184:187], v[142:145]
	v_mfma_f32_16x16x32_bf16 v[138:141], v[134:137], v[184:187], v[138:141]
	v_mfma_f32_16x16x32_bf16 v[110:113], v[118:121], v[192:195], v[110:113]
	v_mfma_f32_16x16x32_bf16 v[106:109], v[134:137], v[192:195], v[106:109]
	v_mfma_f32_16x16x32_bf16 v[94:97], v[118:121], v[200:203], v[94:97]
	v_mfma_f32_16x16x32_bf16 v[90:93], v[134:137], v[200:203], v[90:93]
	v_mfma_f32_16x16x32_bf16 v[78:81], v[118:121], v[230:233], v[78:81]
	v_mfma_f32_16x16x32_bf16 v[74:77], v[134:137], v[230:233], v[74:77]
	v_mfma_f32_16x16x32_bf16 v[126:129], v[146:149], v[180:183], v[126:129]
	v_mfma_f32_16x16x32_bf16 v[122:125], v[168:171], v[180:183], v[122:125]
	v_mfma_f32_16x16x32_bf16 v[102:105], v[146:149], v[188:191], v[102:105]
	v_mfma_f32_16x16x32_bf16 v[98:101], v[168:171], v[188:191], v[98:101]
	v_mfma_f32_16x16x32_bf16 v[86:89], v[146:149], v[196:199], v[86:89]
	v_mfma_f32_16x16x32_bf16 v[82:85], v[168:171], v[196:199], v[82:85]
	v_mfma_f32_16x16x32_bf16 v[70:73], v[146:149], v[208:211], v[70:73]
	v_mfma_f32_16x16x32_bf16 v[66:69], v[168:171], v[208:211], v[66:69]
	v_mfma_f32_16x16x32_bf16 v[126:129], v[150:153], v[184:187], v[126:129]
	v_mfma_f32_16x16x32_bf16 v[122:125], v[172:175], v[184:187], v[122:125]
	v_mfma_f32_16x16x32_bf16 v[102:105], v[150:153], v[192:195], v[102:105]
	v_mfma_f32_16x16x32_bf16 v[98:101], v[172:175], v[192:195], v[98:101]
	v_mfma_f32_16x16x32_bf16 v[86:89], v[150:153], v[200:203], v[86:89]
	v_mfma_f32_16x16x32_bf16 v[82:85], v[172:175], v[200:203], v[82:85]
	v_mfma_f32_16x16x32_bf16 v[70:73], v[150:153], v[230:233], v[70:73]
	v_mfma_f32_16x16x32_bf16 v[66:69], v[172:175], v[230:233], v[66:69]
	s_setprio 0
	s_barrier
	s_add_i32 s47, s88, s6
	s_mov_b32 m0, s47
	ds_read_b128 v[180:183], v178 offset:16384
	ds_read_b128 v[184:187], v178 offset:17408
	ds_read_b128 v[188:191], v178 offset:18432
	ds_read_b128 v[192:195], v178 offset:19456
	ds_read_b128 v[196:199], v178 offset:20480
	ds_read_b128 v[200:203], v178 offset:21504
	ds_read_b128 v[208:211], v178 offset:22528
	ds_read_b128 v[230:233], v178 offset:23552
	global_load_lds_dwordx4 v0, s[40:41]
	s_add_i32 m0, s47, 0x2000
	s_add_u32 s50, s40, 0x80000
	s_addc_u32 s51, s41, 0
	s_add_i32 s47, s89, s6
	global_load_lds_dwordx4 v154, s[40:41]
	s_mov_b32 m0, s47
	s_nop 0
	global_load_lds_dwordx4 v0, s[50:51]
	s_add_i32 m0, s47, 0x2000
	s_nop 0
	global_load_lds_dwordx4 v154, s[50:51]
	s_mov_b32 m0, s8
	s_nop 0
	global_load_lds_dwordx4 v158, s[42:43]
	s_mov_b32 m0, s9
	s_nop 0
	global_load_lds_dwordx4 v156, s[42:43]
	s_waitcnt vmcnt(8)
	s_waitcnt lgkmcnt(0)
	s_barrier
	s_setprio 1
	v_mfma_f32_16x16x32_bf16 v[62:65], v[114:117], v[180:183], v[62:65]
	v_mfma_f32_16x16x32_bf16 v[58:61], v[130:133], v[180:183], v[58:61]
	v_mfma_f32_16x16x32_bf16 v[46:49], v[114:117], v[188:191], v[46:49]
	v_mfma_f32_16x16x32_bf16 v[42:45], v[130:133], v[188:191], v[42:45]
	v_mfma_f32_16x16x32_bf16 v[30:33], v[114:117], v[196:199], v[30:33]
	v_mfma_f32_16x16x32_bf16 v[26:29], v[130:133], v[196:199], v[26:29]
	v_mfma_f32_16x16x32_bf16 v[14:17], v[114:117], v[208:211], v[14:17]
	v_mfma_f32_16x16x32_bf16 v[10:13], v[130:133], v[208:211], v[10:13]
	v_mfma_f32_16x16x32_bf16 v[62:65], v[118:121], v[184:187], v[62:65]
	v_mfma_f32_16x16x32_bf16 v[58:61], v[134:137], v[184:187], v[58:61]
	v_mfma_f32_16x16x32_bf16 v[46:49], v[118:121], v[192:195], v[46:49]
	v_mfma_f32_16x16x32_bf16 v[42:45], v[134:137], v[192:195], v[42:45]
	v_mfma_f32_16x16x32_bf16 v[30:33], v[118:121], v[200:203], v[30:33]
	v_mfma_f32_16x16x32_bf16 v[26:29], v[134:137], v[200:203], v[26:29]
	v_mfma_f32_16x16x32_bf16 v[14:17], v[118:121], v[230:233], v[14:17]
	v_mfma_f32_16x16x32_bf16 v[10:13], v[134:137], v[230:233], v[10:13]
	v_mfma_f32_16x16x32_bf16 v[54:57], v[146:149], v[180:183], v[54:57]
	v_mfma_f32_16x16x32_bf16 v[50:53], v[168:171], v[180:183], v[50:53]
	v_mfma_f32_16x16x32_bf16 v[38:41], v[146:149], v[188:191], v[38:41]
	v_mfma_f32_16x16x32_bf16 v[34:37], v[168:171], v[188:191], v[34:37]
	v_mfma_f32_16x16x32_bf16 v[22:25], v[146:149], v[196:199], v[22:25]
	v_mfma_f32_16x16x32_bf16 v[18:21], v[168:171], v[196:199], v[18:21]
	v_mfma_f32_16x16x32_bf16 v[6:9], v[146:149], v[208:211], v[6:9]
	v_mfma_f32_16x16x32_bf16 v[2:5], v[168:171], v[208:211], v[2:5]
	v_mfma_f32_16x16x32_bf16 v[54:57], v[150:153], v[184:187], v[54:57]
	v_mfma_f32_16x16x32_bf16 v[50:53], v[172:175], v[184:187], v[50:53]
	v_mfma_f32_16x16x32_bf16 v[38:41], v[150:153], v[192:195], v[38:41]
	v_mfma_f32_16x16x32_bf16 v[34:37], v[172:175], v[192:195], v[34:37]
	v_mfma_f32_16x16x32_bf16 v[22:25], v[150:153], v[200:203], v[22:25]
	v_mfma_f32_16x16x32_bf16 v[18:21], v[172:175], v[200:203], v[18:21]
	v_mfma_f32_16x16x32_bf16 v[6:9], v[150:153], v[230:233], v[6:9]
	v_mfma_f32_16x16x32_bf16 v[2:5], v[172:175], v[230:233], v[2:5]
	s_setprio 0
	s_barrier
; #define PG8_STAGE(bufoff, gbase, voff) do { _Pragma("unroll") for (int _i = 0; _i < 2; ++_i) \
;         __builtin_amdgcn_global_load_lds((const unsigned*)((const char*)(gbase) + (voff)[_i]), (PG8_LAS unsigned*)(lds + (bufoff) + ldsw + _i * 8192), 16, 0, 0); } while (0)
; #define PG8_LDA(dst, b, h) do { _Pragma("unroll") for (int m = 0; m < 4; ++m) _Pragma("unroll") for (int k = 0; k < 2; ++k) dst[m][k] = *(const PG8_LAS bf16x8*)(lds + PG8_SA(b, h) + aoff + m * 2048 + k * 1024); } while (0)
; #define PG8_LDB(dst, b, h) do { _Pragma("unroll") for (int n = 0; n < 2; ++n) _Pragma("unroll") for (int k = 0; k < 2; ++k) dst[n][k] = *(const PG8_LAS bf16x8*)(lds + PG8_SB(b, h) + boff + n * 2048 + k * 1024); } while (0)
; #define PG8_MMA(ai, bj, At, Bt) do { __builtin_amdgcn_s_setprio(1); _Pragma("unroll") for (int m = 0; m < 4; ++m) _Pragma("unroll") for (int n = 0; n < 2; ++n) _Pragma("unroll") for (int k = 0; k < 2; ++k) \
;         acc[ai][bj][m][n] = __builtin_amdgcn_mfma_f32_16x16x32_bf16(Bt[n][k], At[m][k], acc[ai][bj][m][n], 0, 0, 0); __builtin_amdgcn_s_setprio(0); } while (0)
; #define PG8_WAIT_V(n) asm volatile("s_waitcnt vmcnt(" #n ")" ::: "memory")
; #define PG8_WAIT_L(n) asm volatile("s_waitcnt lgkmcnt(" #n ")" ::: "memory")
; #define PG8_BAR __builtin_amdgcn_s_barrier()
; #define PG8_SCHED __builtin_amdgcn_sched_barrier(0)
; template <class Epi, class Sched, bool ALIGN_EPI = false, bool SP2 = false>
; __device__ __forceinline__ void gemm_phase(PG8_LAS unsigned char* lds, const Gemm g, const Sched& S, const Epi& E) {
;     ...
;             PG8_LDB(B0, 1, 0); PG8_LDB(B1, 1, 1); PG8_SCHED; PG8_LDA(At, 1, 0); PG8_STAGE(PG8_SA(0, 1), a2 + hstep, voffA);
;             PG8_WAIT_V(8); PG8_WAIT_L(0); PG8_BAR; PG8_MMA(0, 0, At, B0); PG8_MMA(0, 1, At, B1); PG8_BAR; PG8_SCHED;
;             PG8_LDA(At, 1, 1); PG8_STAGE(PG8_SB(1, 0), b3, voffB); PG8_STAGE(PG8_SB(1, 1), b3 + hstep, voffB); PG8_STAGE(PG8_SA(1, 0), a3, voffA);
;             PG8_WAIT_V(8); PG8_WAIT_L(0); PG8_BAR; PG8_MMA(1, 0, At, B0); PG8_MMA(1, 1, At, B1); PG8_BAR; PG8_SCHED;
	s_add_i32 s47, 0, 0x1c000
	ds_read_b128 v[114:117], v244
	ds_read_b128 v[118:121], v244 offset:1024
	ds_read_b128 v[130:133], v244 offset:2048
	ds_read_b128 v[134:137], v244 offset:3072
	ds_read_b128 v[146:149], v245
	ds_read_b128 v[150:153], v245 offset:1024
	ds_read_b128 v[168:171], v245 offset:2048
	ds_read_b128 v[172:175], v245 offset:3072
	s_add_u32 s50, s42, 0x80000
	s_addc_u32 s51, s43, 0
	s_mov_b32 m0, s10
	ds_read_b128 v[180:183], v178 offset:32768
	ds_read_b128 v[184:187], v178 offset:33792
	ds_read_b128 v[188:191], v178 offset:34816
	ds_read_b128 v[192:195], v178 offset:35840
	ds_read_b128 v[196:199], v178 offset:36864
	ds_read_b128 v[200:203], v178 offset:37888
	ds_read_b128 v[208:211], v178 offset:38912
	ds_read_b128 v[230:233], v178 offset:39936
	global_load_lds_dwordx4 v158, s[50:51]
	s_mov_b32 m0, s11
	s_nop 0
	global_load_lds_dwordx4 v156, s[50:51]
	s_waitcnt vmcnt(8)
	s_waitcnt lgkmcnt(0)
	s_barrier
	s_setprio 1
	v_mfma_f32_16x16x32_bf16 v[142:145], v[114:117], v[180:183], v[142:145]
	v_mfma_f32_16x16x32_bf16 v[138:141], v[130:133], v[180:183], v[138:141]
	v_mfma_f32_16x16x32_bf16 v[110:113], v[114:117], v[188:191], v[110:113]
	v_mfma_f32_16x16x32_bf16 v[106:109], v[130:133], v[188:191], v[106:109]
	v_mfma_f32_16x16x32_bf16 v[94:97], v[114:117], v[196:199], v[94:97]
	v_mfma_f32_16x16x32_bf16 v[90:93], v[130:133], v[196:199], v[90:93]
	v_mfma_f32_16x16x32_bf16 v[78:81], v[114:117], v[208:211], v[78:81]
	v_mfma_f32_16x16x32_bf16 v[74:77], v[130:133], v[208:211], v[74:77]
	v_mfma_f32_16x16x32_bf16 v[142:145], v[118:121], v[184:187], v[142:145]
	v_mfma_f32_16x16x32_bf16 v[138:141], v[134:137], v[184:187], v[138:141]
	v_mfma_f32_16x16x32_bf16 v[110:113], v[118:121], v[192:195], v[110:113]
	v_mfma_f32_16x16x32_bf16 v[106:109], v[134:137], v[192:195], v[106:109]
	v_mfma_f32_16x16x32_bf16 v[94:97], v[118:121], v[200:203], v[94:97]
	v_mfma_f32_16x16x32_bf16 v[90:93], v[134:137], v[200:203], v[90:93]
	v_mfma_f32_16x16x32_bf16 v[78:81], v[118:121], v[230:233], v[78:81]
	v_mfma_f32_16x16x32_bf16 v[74:77], v[134:137], v[230:233], v[74:77]
	v_mfma_f32_16x16x32_bf16 v[126:129], v[146:149], v[180:183], v[126:129]
	v_mfma_f32_16x16x32_bf16 v[122:125], v[168:171], v[180:183], v[122:125]
	v_mfma_f32_16x16x32_bf16 v[102:105], v[146:149], v[188:191], v[102:105]
	v_mfma_f32_16x16x32_bf16 v[98:101], v[168:171], v[188:191], v[98:101]
	v_mfma_f32_16x16x32_bf16 v[86:89], v[146:149], v[196:199], v[86:89]
	v_mfma_f32_16x16x32_bf16 v[82:85], v[168:171], v[196:199], v[82:85]
	v_mfma_f32_16x16x32_bf16 v[70:73], v[146:149], v[208:211], v[70:73]
	v_mfma_f32_16x16x32_bf16 v[66:69], v[168:171], v[208:211], v[66:69]
	v_mfma_f32_16x16x32_bf16 v[126:129], v[150:153], v[184:187], v[126:129]
	v_mfma_f32_16x16x32_bf16 v[122:125], v[172:175], v[184:187], v[122:125]
	v_mfma_f32_16x16x32_bf16 v[102:105], v[150:153], v[192:195], v[102:105]
	v_mfma_f32_16x16x32_bf16 v[98:101], v[172:175], v[192:195], v[98:101]
	v_mfma_f32_16x16x32_bf16 v[86:89], v[150:153], v[200:203], v[86:89]
	v_mfma_f32_16x16x32_bf16 v[82:85], v[172:175], v[200:203], v[82:85]
	v_mfma_f32_16x16x32_bf16 v[70:73], v[150:153], v[230:233], v[70:73]
	v_mfma_f32_16x16x32_bf16 v[66:69], v[172:175], v[230:233], v[66:69]
	s_setprio 0
	s_barrier
	s_add_i32 vcc_lo, s90, s6
	s_add_u32 s50, s40, 0x80
	s_addc_u32 s51, s41, 0
	s_mov_b32 m0, vcc_lo
	ds_read_b128 v[180:183], v178 offset:49152
	ds_read_b128 v[184:187], v178 offset:50176
	ds_read_b128 v[188:191], v178 offset:51200
	ds_read_b128 v[192:195], v178 offset:52224
	ds_read_b128 v[196:199], v178 offset:53248
	ds_read_b128 v[200:203], v178 offset:54272
	ds_read_b128 v[208:211], v178 offset:55296
	ds_read_b128 v[230:233], v178 offset:56320
	global_load_lds_dwordx4 v0, s[50:51]
	s_add_i32 m0, vcc_lo, 0x2000
	s_add_i32 vcc_lo, s47, s6
	global_load_lds_dwordx4 v154, s[50:51]
	s_add_u32 s40, s40, 0x80080
	s_addc_u32 s41, s41, 0
	s_mov_b32 m0, vcc_lo
	s_nop 0
	global_load_lds_dwordx4 v0, s[40:41]
	s_add_i32 m0, vcc_lo, 0x2000
	s_nop 0
	global_load_lds_dwordx4 v154, s[40:41]
	s_add_u32 s50, s42, 0x80
	s_addc_u32 s51, s43, 0
	s_mov_b32 m0, s13
	s_nop 0
	global_load_lds_dwordx4 v158, s[50:51]
	s_mov_b32 m0, s25
	s_nop 0
	global_load_lds_dwordx4 v156, s[50:51]
	s_waitcnt vmcnt(8)
	s_waitcnt lgkmcnt(0)
	s_barrier
	s_setprio 1
	v_mfma_f32_16x16x32_bf16 v[62:65], v[114:117], v[180:183], v[62:65]
	v_mfma_f32_16x16x32_bf16 v[58:61], v[130:133], v[180:183], v[58:61]
	v_mfma_f32_16x16x32_bf16 v[46:49], v[114:117], v[188:191], v[46:49]
	v_mfma_f32_16x16x32_bf16 v[42:45], v[130:133], v[188:191], v[42:45]
	v_mfma_f32_16x16x32_bf16 v[30:33], v[114:117], v[196:199], v[30:33]
	v_mfma_f32_16x16x32_bf16 v[26:29], v[130:133], v[196:199], v[26:29]
	v_mfma_f32_16x16x32_bf16 v[14:17], v[114:117], v[208:211], v[14:17]
	v_mfma_f32_16x16x32_bf16 v[10:13], v[130:133], v[208:211], v[10:13]
	v_mfma_f32_16x16x32_bf16 v[62:65], v[118:121], v[184:187], v[62:65]
	v_mfma_f32_16x16x32_bf16 v[58:61], v[134:137], v[184:187], v[58:61]
	v_mfma_f32_16x16x32_bf16 v[46:49], v[118:121], v[192:195], v[46:49]
	v_mfma_f32_16x16x32_bf16 v[42:45], v[134:137], v[192:195], v[42:45]
	v_mfma_f32_16x16x32_bf16 v[30:33], v[118:121], v[200:203], v[30:33]
	v_mfma_f32_16x16x32_bf16 v[26:29], v[134:137], v[200:203], v[26:29]
	v_mfma_f32_16x16x32_bf16 v[14:17], v[118:121], v[230:233], v[14:17]
	v_mfma_f32_16x16x32_bf16 v[10:13], v[134:137], v[230:233], v[10:13]
	v_mfma_f32_16x16x32_bf16 v[54:57], v[146:149], v[180:183], v[54:57]
	v_mfma_f32_16x16x32_bf16 v[50:53], v[168:171], v[180:183], v[50:53]
	v_mfma_f32_16x16x32_bf16 v[38:41], v[146:149], v[188:191], v[38:41]
	v_mfma_f32_16x16x32_bf16 v[34:37], v[168:171], v[188:191], v[34:37]
	v_mfma_f32_16x16x32_bf16 v[22:25], v[146:149], v[196:199], v[22:25]
	v_mfma_f32_16x16x32_bf16 v[18:21], v[168:171], v[196:199], v[18:21]
	v_mfma_f32_16x16x32_bf16 v[6:9], v[146:149], v[208:211], v[6:9]
	v_mfma_f32_16x16x32_bf16 v[2:5], v[168:171], v[208:211], v[2:5]
	v_mfma_f32_16x16x32_bf16 v[54:57], v[150:153], v[184:187], v[54:57]
	v_mfma_f32_16x16x32_bf16 v[50:53], v[172:175], v[184:187], v[50:53]
	v_mfma_f32_16x16x32_bf16 v[38:41], v[150:153], v[192:195], v[38:41]
	v_mfma_f32_16x16x32_bf16 v[34:37], v[172:175], v[192:195], v[34:37]
	v_mfma_f32_16x16x32_bf16 v[22:25], v[150:153], v[200:203], v[22:25]
	v_mfma_f32_16x16x32_bf16 v[18:21], v[172:175], v[200:203], v[18:21]
	v_mfma_f32_16x16x32_bf16 v[6:9], v[150:153], v[230:233], v[6:9]
	v_mfma_f32_16x16x32_bf16 v[2:5], v[172:175], v[230:233], v[2:5]
	s_setprio 0
	s_add_i32 s46, s46, 2
	s_add_u32 s34, s34, 0x100
	s_addc_u32 s35, s35, 0
	s_add_u32 s44, s44, 0x100
	s_addc_u32 s45, s45, 0
	s_cmp_gt_u32 s46, 29
	s_barrier
	s_cbranch_scc0 .LBB0_214
